# R5 QK->SV seam: workgroup-scope L1 invalidate (buffer_inv sc0) instead of the agent-scope one that also emptied the XCD L2
# baseline (speedup 1.0000x reference)
; template <class Epi, class Sched>
; __device__ __forceinline__ void gemm_phase(LAS unsigned char* lds, const Sched& S, const Epi& E) {
;     ...
;     int sR, sRb, sC2;
;     { int R, C; stage_rc(tid * 16, R, C); sR = R; sRb = (R & ~31) + perm32(R & 31); sC2 = C * 2; }
;     const size_t kstep = (size_t)(BK * 2);
;     const unsigned ldsbase = (unsigned)(size_t)lds + (unsigned)wid * 1024u;
;     const int aoff = lds_byte(wr * 64 + fr, fq * 8), boff = lds_byte(wc * 32 + fr, fq * 8);
;     ...
;     int ui = 0;
;     const char* cA; const char* cB; unsigned hA, hB; int nt; unsigned voffA, voffB;
;     { Unit u0; if (!S.next(0, u0)) return;
;       cA = u0.A; cB = u0.B; hA = (unsigned)HALF * u0.lda2; hB = (unsigned)HALF * u0.ldb2; nt = u0.nt;
;       voffA = (unsigned)(sR * u0.lda2 + sC2); voffB = (unsigned)(sRb * u0.ldb2 + sC2); }
;     f32x4 acc[2][2][4][2];
; #pragma unroll
;     for (int a = 0; a < 2; ++a)
; #pragma unroll
;         for (int b = 0; b < 2; ++b)
; #pragma unroll
;             for (int m = 0; m < 4; ++m)
; #pragma unroll
;                 for (int n = 0; n < 2; ++n) acc[a][b][m][n] = (f32x4){0.f, 0.f, 0.f, 0.f};
;     bf16x8 At[4][2], B0[2][2], B1[2][2];
;     PG8_STAGE(PG8_SB(0, 0), cB, voffB, hB / 2); PG8_STAGE(PG8_SB(0, 1), cB + hB, voffB, hB / 2); PG8_STAGE(PG8_SA(0, 0), cA, voffA, hA / 2); PG8_STAGE(PG8_SA(0, 1), cA + hA, voffA, hA / 2);
; __global__ void __launch_bounds__(512, 2) fwd_megakernel(Params Parg) {
;     ...
;             __builtin_amdgcn_fence(__ATOMIC_ACQUIRE, "agent");
;             { PHASE_BEGIN
;               bf16_t* pscr = (bf16_t*)(ws + WS_PSCR + (size_t)(bid >> 1) * (256 * D * 2) + (size_t)(bid & 1) * (CH * 2));
;               const int ib = item & 1, h = (item >> 1) & 3, n = item >> 3;
;               SVSched S{(const char*)(ws + WS_KTQK) + ((size_t)(n * CH + ib * 256) * D + h * 256) * 2, (const char*)(ws + WS_SB) + ((size_t)((h * NCH + n) * 512) * 512) * 2,
;                         (const char*)(ws + WS_VT) + ((size_t)((h * NCH + n) * 512) * 512) * 2, (const char*)pscr, item};
;               EpiSV E; E.o = (bf16_t*)pp->out + (size_t)b * L * 2048; E.dec = WSP(float, WS_DEC); gemm_phase(lds, S, E); }
.LBB0_836:
	v_readlane_b32 s0, v254, 62
	v_readlane_b32 s1, v254, 63
	s_mov_b64 s[4:5], s[0:1]
	s_waitcnt vmcnt(0)
	s_barrier
	s_waitcnt vmcnt(0)
	buffer_inv sc0
	s_load_dwordx4 s[8:11], s[4:5], 0xc8
	s_ashr_i32 s6, s73, 3
	s_lshl_b32 s7, s6, 9
	s_or_b32 s4, s7, s51
	s_ashr_i32 s5, s4, 31
	s_lshl_b32 s12, s72, 9
	s_lshl_b64 s[4:5], s[4:5], 11
	v_mov_b32_e32 v0, v176
	s_waitcnt lgkmcnt(0)
	s_add_u32 s4, s10, s4
	s_addc_u32 s5, s11, s5
	s_add_u32 s34, s4, s12
	v_mov_b32_e32 v0, v176
	s_addc_u32 s35, s5, 0
	s_add_u32 s26, s34, 0x8900000
	v_bfe_i32 v3, v0, 27, 1
	v_lshlrev_b32_e32 v1, 4, v0
	v_lshrrev_b32_e32 v3, 22, v3
	s_addc_u32 s27, s35, 0
	s_lshl_b32 s4, s72, 14
	v_add_u32_e32 v3, v1, v3
	s_add_i32 s4, s4, s7
	v_and_b32_e32 v3, 0xfffffc00, v3
	s_ashr_i32 s5, s4, 31
	v_sub_u32_e32 v1, v1, v3
	s_lshl_b64 s[16:17], s[4:5], 10
	v_ashrrev_i32_e32 v2, 31, v0
	v_lshrrev_b32_e32 v3, 4, v1
	s_add_u32 s7, s10, s16
	v_lshrrev_b32_e32 v2, 26, v2
	v_bitop3_b32 v1, v3, v1, 32 bitop3:0x6c
	s_addc_u32 s24, s11, s17
	v_add_u32_e32 v2, v0, v2
	v_ashrrev_i32_e32 v4, 31, v1
	s_add_u32 s38, s7, 0x10900000
	v_readfirstlane_b32 s22, v0
	v_ashrrev_i32_e32 v2, 6, v2
	v_lshrrev_b32_e32 v4, 26, v4
	s_addc_u32 s39, s24, 0
	s_ashr_i32 s48, s22, 6
	v_lshlrev_b32_e32 v3, 3, v2
	v_add_u32_e32 v4, v1, v4
	v_and_b32_e32 v3, -16, v3
	v_ashrrev_i32_e32 v5, 6, v4
	v_and_b32_e32 v4, 0xc0, v4
	s_lshl_b32 s4, s48, 10
	v_add_u32_e32 v3, v5, v3
	v_sub_u32_e32 v1, v1, v4
	v_and_b32_e32 v5, 3, v5
	s_mov_b32 s5, 0x3fffe0
	s_add_i32 s4, s4, 0
	s_ashr_i32 s23, s22, 8
	v_lshlrev_b32_e32 v2, 5, v2
	v_ashrrev_i16_sdwa v1, v157, sext(v1) dst_sel:DWORD dst_unused:UNUSED_PAD src0_sel:DWORD src1_sel:BYTE_0
	v_lshlrev_b32_e32 v4, 1, v3
	v_lshrrev_b32_e32 v6, 2, v3
	v_and_or_b32 v5, v3, s5, v5
	s_add_i32 s5, s4, 0x10000
	v_bfe_i32 v1, v1, 0, 16
	v_and_b32_e32 v4, 24, v4
	v_and_b32_e32 v6, 4, v6
	v_and_b32_e32 v2, 32, v2
	s_add_u32 s14, s7, 0x10910000
	v_or3_b32 v4, v5, v6, v4
	v_add_lshl_u32 v1, v2, v1, 1
	s_addc_u32 s15, s24, 0
	s_add_i32 s12, s4, 0x12000
	v_lshl_add_u32 v128, v4, 10, v1
	s_mov_b32 m0, s5
	s_nop 0
	global_load_lds_dwordx4 v128, s[38:39]
	s_mov_b32 m0, s12
	s_add_u32 s30, s7, 0x10920000
	global_load_lds_dwordx4 v128, s[14:15]
	s_addc_u32 s31, s24, 0
	s_add_i32 s14, s4, 0x14000
	s_mov_b32 m0, s14
	s_nop 0
	global_load_lds_dwordx4 v128, s[30:31]
	s_add_u32 s30, s7, 0x10930000
	s_addc_u32 s31, s24, 0
	s_add_i32 s15, s4, 0x16000
	s_mov_b32 m0, s15
	s_nop 0
	global_load_lds_dwordx4 v128, s[30:31]
	s_add_u32 s30, s34, 0x8920000
	v_lshl_add_u32 v172, v3, 11, v1
	s_mov_b32 m0, s4
	s_nop 0
	global_load_lds_dwordx4 v172, s[26:27]
	s_addc_u32 s31, s35, 0
	s_add_i32 s24, s4, 0x2000
	s_mov_b32 m0, s24
	s_nop 0
	global_load_lds_dwordx4 v172, s[30:31]
	s_add_u32 s30, s34, 0x8940000
	s_addc_u32 s31, s35, 0
	s_add_i32 s33, s4, 0x4000
	s_mov_b32 m0, s33
	s_nop 0
	global_load_lds_dwordx4 v172, s[30:31]
	s_add_u32 s30, s34, 0x8960000
	s_addc_u32 s31, s35, 0
	s_add_i32 s34, s4, 0x6000
	s_mov_b32 m0, s34
	s_nop 0
	global_load_lds_dwordx4 v172, s[30:31]
	s_cmp_eq_u32 s23, 1
	s_cselect_b64 s[40:41], -1, 0
	s_cmp_lg_u32 s23, 1
	s_cbranch_scc1 .LBB0_838
	s_barrier
